# residual+LN epilogue: row-statistics xor-16/xor-32 hops via v_permlane16/32_swap instead of ds_bpermute_b32 (on top of the combined build)
# speedup vs baseline: 1.0040x; 1.0040x over previous
;   __device__ __forceinline__ void operator()(f32x4 (&acc)[2][2][4][2], int pm, int pn, int wr_, int wc_, int fr_, int fq_, bf16_t* shm, int tid) const {
;     ...
;             s1[ai * 4 + m] += (xv[0] + xv[1]) + (xv[2] + xv[3]);
;             s2[ai * 4 + m] += (xv[0] * xv[0] + xv[1] * xv[1]) + (xv[2] * xv[2] + xv[3] * xv[3]);
;           }
;       }
; #pragma unroll
;     for (int i = 0; i < 8; ++i) {
;       s1[i] += __shfl_xor(s1[i], 16); s1[i] += __shfl_xor(s1[i], 32);
;       s2[i] += __shfl_xor(s2[i], 16); s2[i] += __shfl_xor(s2[i], 32);
;       if (fq == 0) red[((i >> 2) * 128 + wr * 64 + (i & 3) * 16 + fr) * 4 + wc] = (f2_t){s1[i], s2[i]};
.LBB0_200:
	v_mov_b32_e32 v134, v4
	v_mov_b32_e32 v135, v2
	v_mov_b32_e32 v136, v5
	v_mov_b32_e32 v137, v2
	v_pk_add_f32 v[138:139], v[134:135], v[136:137]
	v_pk_mul_f32 v[134:135], v[134:135], v[136:137]
	v_pk_mul_f32 v[136:137], v[2:3], v[2:3]
	v_mov_b32_e32 v139, v135
	v_pk_add_f32 v[134:135], v[2:3], v[2:3] op_sel:[1,0]
	v_mul_f32_e32 v136, v4, v4
	v_mov_b32_e32 v135, v137
	v_pk_fma_f32 v[136:137], v[4:5], v[4:5], v[136:137] op_sel_hi:[1,1,0]
	v_pk_add_f32 v[134:135], v[134:135], v[138:139]
	v_mov_b32_e32 v136, v1
	v_pk_add_f32 v[134:135], v[134:135], v[136:137]
	v_mul_f32_e32 v137, v30, v30
	v_mul_f32_e32 v139, v31, v31
	v_mul_f32_e32 v141, v32, v32
	v_mul_f32_e32 v153, v33, v33
	v_mov_b32_e32 v136, v30
	v_mov_b32_e32 v138, v31
	v_mov_b32_e32 v140, v32
	v_mov_b32_e32 v152, v33
	v_pk_add_f32 v[136:137], v[136:137], v[138:139]
	v_pk_add_f32 v[138:139], v[140:141], v[152:153]
	v_mul_f32_e32 v141, v64, v64
	v_pk_add_f32 v[136:137], v[136:137], v[138:139]
	v_mul_f32_e32 v139, v63, v63
	v_pk_add_f32 v[134:135], v[134:135], v[136:137]
	v_mul_f32_e32 v137, v62, v62
	v_mul_f32_e32 v153, v65, v65
	v_mov_b32_e32 v136, v62
	v_mov_b32_e32 v138, v63
	v_mov_b32_e32 v140, v64
	v_mov_b32_e32 v152, v65
	v_pk_add_f32 v[136:137], v[136:137], v[138:139]
	v_pk_add_f32 v[138:139], v[140:141], v[152:153]
	v_mul_f32_e32 v141, v100, v100
	v_pk_add_f32 v[136:137], v[136:137], v[138:139]
	v_mul_f32_e32 v139, v99, v99
	v_pk_add_f32 v[134:135], v[134:135], v[136:137]
	v_mul_f32_e32 v137, v98, v98
	v_mul_f32_e32 v153, v101, v101
	v_mov_b32_e32 v136, v98
	v_mov_b32_e32 v138, v99
	v_mov_b32_e32 v140, v100
	v_mov_b32_e32 v152, v101
	v_pk_add_f32 v[136:137], v[136:137], v[138:139]
	v_pk_add_f32 v[138:139], v[140:141], v[152:153]
	v_readlane_b32 s6, v253, 26
	v_pk_add_f32 v[136:137], v[136:137], v[138:139]
	v_pk_add_f32 v[136:137], v[134:135], v[136:137]
	v_and_b32_e32 v131, 64, v226
	v_xor_b32_e32 v130, 16, v226
	v_add_u32_e32 v132, 64, v131
	v_cmp_lt_i32_e32 vcc, v130, v132
	v_xor_b32_e32 v133, 32, v226
	v_or_b32_e32 v154, v214, v149
	v_cndmask_b32_e32 v130, v226, v130, vcc
	v_lshlrev_b32_e32 v134, 2, v130
	v_mov_b32_e32 v130, v136
	v_mov_b32_e32 v131, v137
	s_nop 1
	v_permlane16_swap_b32_e32 v130, v136
	v_permlane16_swap_b32_e32 v131, v137
	v_cmp_lt_i32_e32 vcc, v133, v132
	s_waitcnt lgkmcnt(0)
	v_pk_add_f32 v[130:131], v[136:137], v[130:131]
	v_cndmask_b32_e32 v132, v226, v133, vcc
	v_lshlrev_b32_e32 v135, 2, v132
	v_mov_b32_e32 v132, v130
	v_mov_b32_e32 v133, v131
	s_nop 1
	v_permlane32_swap_b32_e32 v132, v130
	v_permlane32_swap_b32_e32 v133, v131
	v_lshl_add_u32 v136, v215, 3, s6
	v_cmp_eq_u32_e32 vcc, 0, v216
	v_lshl_add_u32 v137, v154, 5, v136
	s_and_saveexec_b64 s[6:7], vcc
	s_cbranch_execz .LBB0_202
	s_waitcnt lgkmcnt(0)
	v_pk_add_f32 v[130:131], v[130:131], v[132:133]
	ds_write_b64 v137, v[130:131]
.LBB0_202:
	s_or_b64 exec, exec, s[6:7]
	v_mov_b32_e32 v130, v8
	v_mov_b32_e32 v131, v6
	s_waitcnt lgkmcnt(1)
	v_mov_b32_e32 v132, v9
	s_waitcnt lgkmcnt(0)
	v_mov_b32_e32 v133, v6
	v_pk_add_f32 v[138:139], v[130:131], v[132:133]
	v_pk_mul_f32 v[130:131], v[130:131], v[132:133]
	v_pk_mul_f32 v[132:133], v[6:7], v[6:7]
	v_mov_b32_e32 v139, v131
	v_pk_add_f32 v[130:131], v[6:7], v[6:7] op_sel:[1,0]
	v_mul_f32_e32 v132, v8, v8
	v_mov_b32_e32 v131, v133
	v_pk_fma_f32 v[132:133], v[8:9], v[8:9], v[132:133] op_sel_hi:[1,1,0]
	v_pk_add_f32 v[130:131], v[130:131], v[138:139]
	v_mov_b32_e32 v132, v1
	v_pk_add_f32 v[130:131], v[130:131], v[132:133]
	v_mul_f32_e32 v133, v38, v38
	v_mul_f32_e32 v139, v39, v39
	v_mul_f32_e32 v141, v40, v40
	v_mul_f32_e32 v143, v41, v41
	v_mov_b32_e32 v132, v38
	v_mov_b32_e32 v138, v39
	v_mov_b32_e32 v140, v40
	v_mov_b32_e32 v142, v41
	v_pk_add_f32 v[132:133], v[132:133], v[138:139]
	v_pk_add_f32 v[138:139], v[140:141], v[142:143]
	v_mul_f32_e32 v141, v72, v72
	v_pk_add_f32 v[132:133], v[132:133], v[138:139]
	v_mul_f32_e32 v139, v71, v71
	v_pk_add_f32 v[130:131], v[130:131], v[132:133]
	v_mul_f32_e32 v133, v70, v70
	v_mul_f32_e32 v143, v73, v73
	v_mov_b32_e32 v132, v70
	v_mov_b32_e32 v138, v71
	v_mov_b32_e32 v140, v72
	v_mov_b32_e32 v142, v73
	v_pk_add_f32 v[132:133], v[132:133], v[138:139]
	v_pk_add_f32 v[138:139], v[140:141], v[142:143]
	v_mul_f32_e32 v141, v108, v108
	v_pk_add_f32 v[132:133], v[132:133], v[138:139]
	v_mul_f32_e32 v139, v107, v107
	v_pk_add_f32 v[130:131], v[130:131], v[132:133]
	v_mul_f32_e32 v133, v106, v106
	v_mul_f32_e32 v143, v109, v109
	v_mov_b32_e32 v132, v106
	v_mov_b32_e32 v138, v107
	v_mov_b32_e32 v140, v108
	v_mov_b32_e32 v142, v109
	v_pk_add_f32 v[132:133], v[132:133], v[138:139]
	v_pk_add_f32 v[138:139], v[140:141], v[142:143]
	s_nop 0
	v_pk_add_f32 v[132:133], v[132:133], v[138:139]
	s_nop 0
	v_pk_add_f32 v[130:131], v[130:131], v[132:133]
	v_mov_b32_e32 v132, v130
	v_mov_b32_e32 v133, v131
	s_nop 1
	v_permlane16_swap_b32_e32 v132, v130
	v_permlane16_swap_b32_e32 v133, v131
	s_waitcnt lgkmcnt(0)
	v_pk_add_f32 v[130:131], v[130:131], v[132:133]
	v_mov_b32_e32 v132, v130
	v_mov_b32_e32 v133, v131
	s_nop 1
	v_permlane32_swap_b32_e32 v132, v130
	v_permlane32_swap_b32_e32 v133, v131
	s_and_saveexec_b64 s[6:7], vcc
	s_cbranch_execz .LBB0_204
	s_waitcnt lgkmcnt(0)
	v_pk_add_f32 v[130:131], v[130:131], v[132:133]
	ds_write_b64 v137, v[130:131] offset:512
;   __device__ __forceinline__ void operator()(f32x4 (&acc)[2][2][4][2], int pm, int pn, int wr_, int wc_, int fr_, int fq_, bf16_t* shm, int tid) const {
;     ...
;             s1[ai * 4 + m] += (xv[0] + xv[1]) + (xv[2] + xv[3]);
;             s2[ai * 4 + m] += (xv[0] * xv[0] + xv[1] * xv[1]) + (xv[2] * xv[2] + xv[3] * xv[3]);
;           }
;       }
; #pragma unroll
;     for (int i = 0; i < 8; ++i) {
;       s1[i] += __shfl_xor(s1[i], 16); s1[i] += __shfl_xor(s1[i], 32);
;       s2[i] += __shfl_xor(s2[i], 16); s2[i] += __shfl_xor(s2[i], 32);
;       if (fq == 0) red[((i >> 2) * 128 + wr * 64 + (i & 3) * 16 + fr) * 4 + wc] = (f2_t){s1[i], s2[i]};
.LBB0_204:
	s_or_b64 exec, exec, s[6:7]
	v_mov_b32_e32 v130, v12
	v_mov_b32_e32 v131, v10
	s_waitcnt lgkmcnt(1)
	v_mov_b32_e32 v132, v13
	s_waitcnt lgkmcnt(0)
	v_mov_b32_e32 v133, v10
	v_pk_add_f32 v[138:139], v[130:131], v[132:133]
	v_pk_mul_f32 v[130:131], v[130:131], v[132:133]
	v_pk_mul_f32 v[132:133], v[10:11], v[10:11]
	v_mov_b32_e32 v139, v131
	v_pk_add_f32 v[130:131], v[10:11], v[10:11] op_sel:[1,0]
	v_mul_f32_e32 v132, v12, v12
	v_mov_b32_e32 v131, v133
	v_pk_fma_f32 v[132:133], v[12:13], v[12:13], v[132:133] op_sel_hi:[1,1,0]
	v_pk_add_f32 v[130:131], v[130:131], v[138:139]
	v_mov_b32_e32 v132, v1
	v_pk_add_f32 v[130:131], v[130:131], v[132:133]
	v_mul_f32_e32 v133, v42, v42
	v_mul_f32_e32 v139, v43, v43
	v_mul_f32_e32 v141, v44, v44
	v_mul_f32_e32 v143, v45, v45
	v_mov_b32_e32 v132, v42
	v_mov_b32_e32 v138, v43
	v_mov_b32_e32 v140, v44
	v_mov_b32_e32 v142, v45
	v_pk_add_f32 v[132:133], v[132:133], v[138:139]
	v_pk_add_f32 v[138:139], v[140:141], v[142:143]
	v_mul_f32_e32 v141, v76, v76
	v_pk_add_f32 v[132:133], v[132:133], v[138:139]
	v_mul_f32_e32 v139, v75, v75
	v_pk_add_f32 v[130:131], v[130:131], v[132:133]
	v_mul_f32_e32 v133, v74, v74
	v_mul_f32_e32 v143, v77, v77
	v_mov_b32_e32 v132, v74
	v_mov_b32_e32 v138, v75
	v_mov_b32_e32 v140, v76
	v_mov_b32_e32 v142, v77
	v_pk_add_f32 v[132:133], v[132:133], v[138:139]
	v_pk_add_f32 v[138:139], v[140:141], v[142:143]
	v_mul_f32_e32 v141, v112, v112
	v_pk_add_f32 v[132:133], v[132:133], v[138:139]
	v_mul_f32_e32 v139, v111, v111
	v_pk_add_f32 v[130:131], v[130:131], v[132:133]
	v_mul_f32_e32 v133, v110, v110
	v_mul_f32_e32 v143, v113, v113
	v_mov_b32_e32 v132, v110
	v_mov_b32_e32 v138, v111
	v_mov_b32_e32 v140, v112
	v_mov_b32_e32 v142, v113
	v_pk_add_f32 v[132:133], v[132:133], v[138:139]
	v_pk_add_f32 v[138:139], v[140:141], v[142:143]
	s_nop 0
	v_pk_add_f32 v[132:133], v[132:133], v[138:139]
	s_nop 0
	v_pk_add_f32 v[130:131], v[130:131], v[132:133]
	v_mov_b32_e32 v132, v130
	v_mov_b32_e32 v133, v131
	s_nop 1
	v_permlane16_swap_b32_e32 v132, v130
	v_permlane16_swap_b32_e32 v133, v131
	s_waitcnt lgkmcnt(0)
	v_pk_add_f32 v[130:131], v[130:131], v[132:133]
	v_mov_b32_e32 v132, v130
	v_mov_b32_e32 v133, v131
	s_nop 1
	v_permlane32_swap_b32_e32 v132, v130
	v_permlane32_swap_b32_e32 v133, v131
	s_and_saveexec_b64 s[6:7], vcc
	s_cbranch_execz .LBB0_206
	s_waitcnt lgkmcnt(0)
	v_pk_add_f32 v[130:131], v[130:131], v[132:133]
	ds_write_b64 v137, v[130:131] offset:1024
.LBB0_206:
	s_or_b64 exec, exec, s[6:7]
	v_mov_b32_e32 v130, v16
	v_mov_b32_e32 v131, v14
	s_waitcnt lgkmcnt(1)
	v_mov_b32_e32 v132, v17
	s_waitcnt lgkmcnt(0)
	v_mov_b32_e32 v133, v14
	v_pk_add_f32 v[138:139], v[130:131], v[132:133]
	v_pk_mul_f32 v[130:131], v[130:131], v[132:133]
	v_pk_mul_f32 v[132:133], v[14:15], v[14:15]
	v_mov_b32_e32 v139, v131
	v_pk_add_f32 v[130:131], v[14:15], v[14:15] op_sel:[1,0]
	v_mul_f32_e32 v132, v16, v16
	v_mov_b32_e32 v131, v133
	v_pk_fma_f32 v[132:133], v[16:17], v[16:17], v[132:133] op_sel_hi:[1,1,0]
	v_pk_add_f32 v[130:131], v[130:131], v[138:139]
	v_mov_b32_e32 v132, v1
	v_pk_add_f32 v[130:131], v[130:131], v[132:133]
	v_mul_f32_e32 v133, v46, v46
	v_mul_f32_e32 v139, v47, v47
	v_mul_f32_e32 v141, v48, v48
	v_mul_f32_e32 v143, v49, v49
	v_mov_b32_e32 v132, v46
	v_mov_b32_e32 v138, v47
	v_mov_b32_e32 v140, v48
	v_mov_b32_e32 v142, v49
	v_pk_add_f32 v[132:133], v[132:133], v[138:139]
	v_pk_add_f32 v[138:139], v[140:141], v[142:143]
	v_mul_f32_e32 v141, v80, v80
	v_pk_add_f32 v[132:133], v[132:133], v[138:139]
	v_mul_f32_e32 v139, v79, v79
	v_pk_add_f32 v[130:131], v[130:131], v[132:133]
	v_mul_f32_e32 v133, v78, v78
	v_mul_f32_e32 v143, v81, v81
	v_mov_b32_e32 v132, v78
	v_mov_b32_e32 v138, v79
	v_mov_b32_e32 v140, v80
	v_mov_b32_e32 v142, v81
	v_pk_add_f32 v[132:133], v[132:133], v[138:139]
	v_pk_add_f32 v[138:139], v[140:141], v[142:143]
	v_mul_f32_e32 v141, v116, v116
	v_pk_add_f32 v[132:133], v[132:133], v[138:139]
	v_mul_f32_e32 v139, v115, v115
	v_pk_add_f32 v[130:131], v[130:131], v[132:133]
	v_mul_f32_e32 v133, v114, v114
	v_mul_f32_e32 v143, v117, v117
	v_mov_b32_e32 v132, v114
	v_mov_b32_e32 v138, v115
	v_mov_b32_e32 v140, v116
	v_mov_b32_e32 v142, v117
	v_pk_add_f32 v[132:133], v[132:133], v[138:139]
	v_pk_add_f32 v[138:139], v[140:141], v[142:143]
	s_nop 0
	v_pk_add_f32 v[132:133], v[132:133], v[138:139]
	s_nop 0
	v_pk_add_f32 v[130:131], v[130:131], v[132:133]
	v_mov_b32_e32 v132, v130
	v_mov_b32_e32 v133, v131
	s_nop 1
	v_permlane16_swap_b32_e32 v132, v130
	v_permlane16_swap_b32_e32 v133, v131
	s_waitcnt lgkmcnt(0)
	v_pk_add_f32 v[130:131], v[130:131], v[132:133]
	v_mov_b32_e32 v132, v130
	v_mov_b32_e32 v133, v131
	s_nop 1
	v_permlane32_swap_b32_e32 v132, v130
	v_permlane32_swap_b32_e32 v133, v131
	s_and_saveexec_b64 s[6:7], vcc
	s_cbranch_execz .LBB0_208
	s_waitcnt lgkmcnt(0)
	v_pk_add_f32 v[130:131], v[130:131], v[132:133]
	ds_write_b64 v137, v[130:131] offset:1536
;   __device__ __forceinline__ void operator()(f32x4 (&acc)[2][2][4][2], int pm, int pn, int wr_, int wc_, int fr_, int fq_, bf16_t* shm, int tid) const {
;     ...
;             s1[ai * 4 + m] += (xv[0] + xv[1]) + (xv[2] + xv[3]);
;             s2[ai * 4 + m] += (xv[0] * xv[0] + xv[1] * xv[1]) + (xv[2] * xv[2] + xv[3] * xv[3]);
;           }
;       }
; #pragma unroll
;     for (int i = 0; i < 8; ++i) {
;       s1[i] += __shfl_xor(s1[i], 16); s1[i] += __shfl_xor(s1[i], 32);
;       s2[i] += __shfl_xor(s2[i], 16); s2[i] += __shfl_xor(s2[i], 32);
;       if (fq == 0) red[((i >> 2) * 128 + wr * 64 + (i & 3) * 16 + fr) * 4 + wc] = (f2_t){s1[i], s2[i]};
.LBB0_208:
	s_or_b64 exec, exec, s[6:7]
	v_mov_b32_e32 v130, v20
	v_mov_b32_e32 v131, v18
	s_waitcnt lgkmcnt(1)
	v_mov_b32_e32 v132, v21
	s_waitcnt lgkmcnt(0)
	v_mov_b32_e32 v133, v18
	v_pk_add_f32 v[138:139], v[130:131], v[132:133]
	v_pk_mul_f32 v[130:131], v[130:131], v[132:133]
	v_pk_mul_f32 v[132:133], v[18:19], v[18:19]
	v_mov_b32_e32 v139, v131
	v_pk_add_f32 v[130:131], v[18:19], v[18:19] op_sel:[1,0]
	v_mul_f32_e32 v132, v20, v20
	v_mov_b32_e32 v131, v133
	v_pk_fma_f32 v[132:133], v[20:21], v[20:21], v[132:133] op_sel_hi:[1,1,0]
	v_pk_add_f32 v[130:131], v[130:131], v[138:139]
	v_mov_b32_e32 v132, v1
	v_pk_add_f32 v[130:131], v[130:131], v[132:133]
	v_mul_f32_e32 v133, v50, v50
	v_mul_f32_e32 v139, v51, v51
	v_mul_f32_e32 v141, v52, v52
	v_mul_f32_e32 v143, v53, v53
	v_mov_b32_e32 v132, v50
	v_mov_b32_e32 v138, v51
	v_mov_b32_e32 v140, v52
	v_mov_b32_e32 v142, v53
	v_pk_add_f32 v[132:133], v[132:133], v[138:139]
	v_pk_add_f32 v[138:139], v[140:141], v[142:143]
	v_mul_f32_e32 v141, v84, v84
	v_pk_add_f32 v[132:133], v[132:133], v[138:139]
	v_mul_f32_e32 v139, v83, v83
	v_pk_add_f32 v[130:131], v[130:131], v[132:133]
	v_mul_f32_e32 v133, v82, v82
	v_mul_f32_e32 v143, v85, v85
	v_mov_b32_e32 v132, v82
	v_mov_b32_e32 v138, v83
	v_mov_b32_e32 v140, v84
	v_mov_b32_e32 v142, v85
	v_pk_add_f32 v[132:133], v[132:133], v[138:139]
	v_pk_add_f32 v[138:139], v[140:141], v[142:143]
	v_mul_f32_e32 v141, v124, v124
	v_pk_add_f32 v[132:133], v[132:133], v[138:139]
	v_mul_f32_e32 v139, v123, v123
	v_pk_add_f32 v[130:131], v[130:131], v[132:133]
	v_mul_f32_e32 v133, v122, v122
	v_mul_f32_e32 v143, v125, v125
	v_mov_b32_e32 v132, v122
	v_mov_b32_e32 v138, v123
	v_mov_b32_e32 v140, v124
	v_mov_b32_e32 v142, v125
	v_pk_add_f32 v[132:133], v[132:133], v[138:139]
	v_pk_add_f32 v[138:139], v[140:141], v[142:143]
	v_add_u32_e32 v137, v214, v149
	v_pk_add_f32 v[132:133], v[132:133], v[138:139]
	v_lshl_add_u32 v136, v137, 5, v136
	v_pk_add_f32 v[130:131], v[130:131], v[132:133]
	v_mov_b32_e32 v132, v130
	v_mov_b32_e32 v133, v131
	s_nop 1
	v_permlane16_swap_b32_e32 v132, v130
	v_permlane16_swap_b32_e32 v133, v131
	s_waitcnt lgkmcnt(0)
	v_pk_add_f32 v[130:131], v[130:131], v[132:133]
	v_mov_b32_e32 v132, v130
	v_mov_b32_e32 v133, v131
	s_nop 1
	v_permlane32_swap_b32_e32 v132, v130
	v_permlane32_swap_b32_e32 v133, v131
	s_and_saveexec_b64 s[6:7], vcc
	s_cbranch_execz .LBB0_210
	s_waitcnt lgkmcnt(0)
	v_pk_add_f32 v[130:131], v[130:131], v[132:133]
	ds_write_b64 v136, v[130:131] offset:4096
.LBB0_210:
	s_or_b64 exec, exec, s[6:7]
	v_mov_b32_e32 v130, v24
	v_mov_b32_e32 v131, v22
	s_waitcnt lgkmcnt(1)
	v_mov_b32_e32 v132, v25
	s_waitcnt lgkmcnt(0)
	v_mov_b32_e32 v133, v22
	v_pk_add_f32 v[138:139], v[130:131], v[132:133]
	v_pk_mul_f32 v[130:131], v[130:131], v[132:133]
	v_pk_mul_f32 v[132:133], v[22:23], v[22:23]
	v_mov_b32_e32 v139, v131
	v_pk_add_f32 v[130:131], v[22:23], v[22:23] op_sel:[1,0]
	v_mul_f32_e32 v132, v24, v24
	v_mov_b32_e32 v131, v133
	v_pk_fma_f32 v[132:133], v[24:25], v[24:25], v[132:133] op_sel_hi:[1,1,0]
	v_pk_add_f32 v[130:131], v[130:131], v[138:139]
	v_mov_b32_e32 v132, v1
	v_pk_add_f32 v[130:131], v[130:131], v[132:133]
	v_mul_f32_e32 v133, v54, v54
	v_mul_f32_e32 v139, v55, v55
	v_mul_f32_e32 v141, v56, v56
	v_mul_f32_e32 v143, v57, v57
	v_mov_b32_e32 v132, v54
	v_mov_b32_e32 v138, v55
	v_mov_b32_e32 v140, v56
	v_mov_b32_e32 v142, v57
	v_pk_add_f32 v[132:133], v[132:133], v[138:139]
	v_pk_add_f32 v[138:139], v[140:141], v[142:143]
	v_mul_f32_e32 v141, v88, v88
	v_pk_add_f32 v[132:133], v[132:133], v[138:139]
	v_mul_f32_e32 v139, v87, v87
	v_pk_add_f32 v[130:131], v[130:131], v[132:133]
	v_mul_f32_e32 v133, v86, v86
	v_mul_f32_e32 v143, v89, v89
	v_mov_b32_e32 v132, v86
	v_mov_b32_e32 v138, v87
	v_mov_b32_e32 v140, v88
	v_mov_b32_e32 v142, v89
	v_pk_add_f32 v[132:133], v[132:133], v[138:139]
	v_pk_add_f32 v[138:139], v[140:141], v[142:143]
	v_mul_f32_e32 v141, v128, v128
	v_pk_add_f32 v[132:133], v[132:133], v[138:139]
	v_mul_f32_e32 v139, v127, v127
	v_pk_add_f32 v[130:131], v[130:131], v[132:133]
	v_mul_f32_e32 v133, v126, v126
	v_mul_f32_e32 v143, v129, v129
	v_mov_b32_e32 v132, v126
	v_mov_b32_e32 v138, v127
	v_mov_b32_e32 v140, v128
	v_mov_b32_e32 v142, v129
	v_pk_add_f32 v[132:133], v[132:133], v[138:139]
	v_pk_add_f32 v[138:139], v[140:141], v[142:143]
	s_nop 0
	v_pk_add_f32 v[132:133], v[132:133], v[138:139]
	s_nop 0
	v_pk_add_f32 v[130:131], v[130:131], v[132:133]
	v_mov_b32_e32 v132, v130
	v_mov_b32_e32 v133, v131
	s_nop 1
	v_permlane16_swap_b32_e32 v132, v130
	v_permlane16_swap_b32_e32 v133, v131
	s_waitcnt lgkmcnt(0)
	v_pk_add_f32 v[130:131], v[130:131], v[132:133]
	v_mov_b32_e32 v132, v130
	v_mov_b32_e32 v133, v131
	s_nop 1
	v_permlane32_swap_b32_e32 v132, v130
	v_permlane32_swap_b32_e32 v133, v131
	s_and_saveexec_b64 s[6:7], vcc
	s_cbranch_execz .LBB0_212
	s_waitcnt lgkmcnt(0)
	v_pk_add_f32 v[130:131], v[130:131], v[132:133]
	ds_write_b64 v136, v[130:131] offset:4608
;   __device__ __forceinline__ void operator()(f32x4 (&acc)[2][2][4][2], int pm, int pn, int wr_, int wc_, int fr_, int fq_, bf16_t* shm, int tid) const {
;     ...
;             s1[ai * 4 + m] += (xv[0] + xv[1]) + (xv[2] + xv[3]);
;             s2[ai * 4 + m] += (xv[0] * xv[0] + xv[1] * xv[1]) + (xv[2] * xv[2] + xv[3] * xv[3]);
;           }
;       }
; #pragma unroll
;     for (int i = 0; i < 8; ++i) {
;       s1[i] += __shfl_xor(s1[i], 16); s1[i] += __shfl_xor(s1[i], 32);
;       s2[i] += __shfl_xor(s2[i], 16); s2[i] += __shfl_xor(s2[i], 32);
;       if (fq == 0) red[((i >> 2) * 128 + wr * 64 + (i & 3) * 16 + fr) * 4 + wc] = (f2_t){s1[i], s2[i]};
.LBB0_212:
	s_or_b64 exec, exec, s[6:7]
	v_mov_b32_e32 v130, v28
	v_mov_b32_e32 v131, v26
	s_waitcnt lgkmcnt(1)
	v_mov_b32_e32 v132, v29
	s_waitcnt lgkmcnt(0)
	v_mov_b32_e32 v133, v26
	v_pk_add_f32 v[138:139], v[130:131], v[132:133]
	v_pk_mul_f32 v[130:131], v[130:131], v[132:133]
	v_pk_mul_f32 v[132:133], v[26:27], v[26:27]
	v_mov_b32_e32 v139, v131
	v_pk_add_f32 v[130:131], v[26:27], v[26:27] op_sel:[1,0]
	v_mul_f32_e32 v132, v28, v28
	v_mov_b32_e32 v131, v133
	v_pk_fma_f32 v[132:133], v[28:29], v[28:29], v[132:133] op_sel_hi:[1,1,0]
	v_pk_add_f32 v[130:131], v[130:131], v[138:139]
	v_mov_b32_e32 v132, v1
	v_pk_add_f32 v[130:131], v[130:131], v[132:133]
	v_mul_f32_e32 v133, v58, v58
	v_mul_f32_e32 v139, v59, v59
	v_mul_f32_e32 v141, v60, v60
	v_mul_f32_e32 v143, v61, v61
	v_mov_b32_e32 v132, v58
	v_mov_b32_e32 v138, v59
	v_mov_b32_e32 v140, v60
	v_mov_b32_e32 v142, v61
	v_pk_add_f32 v[132:133], v[132:133], v[138:139]
	v_pk_add_f32 v[138:139], v[140:141], v[142:143]
	v_mul_f32_e32 v141, v92, v92
	v_pk_add_f32 v[132:133], v[132:133], v[138:139]
	v_mul_f32_e32 v139, v91, v91
	v_pk_add_f32 v[130:131], v[130:131], v[132:133]
	v_mul_f32_e32 v133, v90, v90
	v_mul_f32_e32 v143, v93, v93
	v_mov_b32_e32 v132, v90
	v_mov_b32_e32 v138, v91
	v_mov_b32_e32 v140, v92
	v_mov_b32_e32 v142, v93
	v_pk_add_f32 v[132:133], v[132:133], v[138:139]
	v_pk_add_f32 v[138:139], v[140:141], v[142:143]
	v_mul_f32_e32 v141, v120, v120
	v_pk_add_f32 v[132:133], v[132:133], v[138:139]
	v_mul_f32_e32 v139, v119, v119
	v_pk_add_f32 v[130:131], v[130:131], v[132:133]
	v_mul_f32_e32 v133, v118, v118
	v_mul_f32_e32 v143, v121, v121
	v_mov_b32_e32 v132, v118
	v_mov_b32_e32 v138, v119
	v_mov_b32_e32 v140, v120
	v_mov_b32_e32 v142, v121
	v_pk_add_f32 v[132:133], v[132:133], v[138:139]
	v_pk_add_f32 v[138:139], v[140:141], v[142:143]
	s_nop 0
	v_pk_add_f32 v[132:133], v[132:133], v[138:139]
	s_nop 0
	v_pk_add_f32 v[130:131], v[130:131], v[132:133]
	v_mov_b32_e32 v132, v130
	v_mov_b32_e32 v133, v131
	s_nop 1
	v_permlane16_swap_b32_e32 v132, v130
	v_permlane16_swap_b32_e32 v133, v131
	s_waitcnt lgkmcnt(0)
	v_pk_add_f32 v[130:131], v[130:131], v[132:133]
	v_mov_b32_e32 v132, v130
	v_mov_b32_e32 v133, v131
	s_nop 1
	v_permlane32_swap_b32_e32 v132, v130
	v_permlane32_swap_b32_e32 v133, v131
	s_and_saveexec_b64 s[6:7], vcc
	s_cbranch_execz .LBB0_214
	s_waitcnt lgkmcnt(0)
	v_pk_add_f32 v[130:131], v[130:131], v[132:133]
	ds_write_b64 v136, v[130:131] offset:5120
.LBB0_214:
	s_or_b64 exec, exec, s[6:7]
	v_mov_b32_e32 v130, v36
	v_mov_b32_e32 v131, v34
	s_waitcnt lgkmcnt(1)
	v_mov_b32_e32 v132, v37
	s_waitcnt lgkmcnt(0)
	v_mov_b32_e32 v133, v34
	v_pk_add_f32 v[138:139], v[130:131], v[132:133]
	v_pk_mul_f32 v[130:131], v[130:131], v[132:133]
	v_pk_mul_f32 v[132:133], v[34:35], v[34:35]
	v_mov_b32_e32 v139, v131
	v_pk_add_f32 v[130:131], v[34:35], v[34:35] op_sel:[1,0]
	v_mul_f32_e32 v132, v36, v36
	v_mov_b32_e32 v131, v133
	v_pk_fma_f32 v[132:133], v[36:37], v[36:37], v[132:133] op_sel_hi:[1,1,0]
	v_pk_add_f32 v[130:131], v[130:131], v[138:139]
	v_mov_b32_e32 v132, v1
	v_pk_add_f32 v[130:131], v[130:131], v[132:133]
	v_mul_f32_e32 v133, v66, v66
	v_mul_f32_e32 v139, v67, v67
	v_mul_f32_e32 v141, v68, v68
	v_mul_f32_e32 v143, v69, v69
	v_mov_b32_e32 v132, v66
	v_mov_b32_e32 v138, v67
	v_mov_b32_e32 v140, v68
	v_mov_b32_e32 v142, v69
	v_pk_add_f32 v[132:133], v[132:133], v[138:139]
	v_pk_add_f32 v[138:139], v[140:141], v[142:143]
	v_mul_f32_e32 v141, v104, v104
	v_pk_add_f32 v[132:133], v[132:133], v[138:139]
	v_mul_f32_e32 v139, v103, v103
	v_pk_add_f32 v[130:131], v[130:131], v[132:133]
	v_mul_f32_e32 v133, v102, v102
	v_mul_f32_e32 v143, v105, v105
	v_mov_b32_e32 v132, v102
	v_mov_b32_e32 v138, v103
	v_mov_b32_e32 v140, v104
	v_mov_b32_e32 v142, v105
	v_pk_add_f32 v[132:133], v[132:133], v[138:139]
	v_pk_add_f32 v[138:139], v[140:141], v[142:143]
	v_mul_f32_e32 v141, v96, v96
	v_pk_add_f32 v[132:133], v[132:133], v[138:139]
	v_mul_f32_e32 v139, v95, v95
	v_pk_add_f32 v[130:131], v[130:131], v[132:133]
	v_mul_f32_e32 v133, v94, v94
	v_mul_f32_e32 v143, v97, v97
	v_mov_b32_e32 v132, v94
	v_mov_b32_e32 v138, v95
	v_mov_b32_e32 v140, v96
	v_mov_b32_e32 v142, v97
	v_pk_add_f32 v[132:133], v[132:133], v[138:139]
	v_pk_add_f32 v[138:139], v[140:141], v[142:143]
	s_nop 0
	v_pk_add_f32 v[132:133], v[132:133], v[138:139]
	s_nop 0
	v_pk_add_f32 v[130:131], v[130:131], v[132:133]
	v_mov_b32_e32 v132, v130
	v_mov_b32_e32 v133, v131
	s_nop 1
	v_permlane16_swap_b32_e32 v132, v130
	v_permlane16_swap_b32_e32 v133, v131
	s_waitcnt lgkmcnt(0)
	v_pk_add_f32 v[130:131], v[130:131], v[132:133]
	v_mov_b32_e32 v132, v130
	v_mov_b32_e32 v133, v131
	s_nop 1
	v_permlane32_swap_b32_e32 v132, v130
	v_permlane32_swap_b32_e32 v133, v131
	s_and_saveexec_b64 s[6:7], vcc
	s_cbranch_execz .LBB0_216
	s_waitcnt lgkmcnt(0)
	v_pk_add_f32 v[130:131], v[130:131], v[132:133]
	ds_write_b64 v136, v[130:131] offset:5632

;   __device__ __forceinline__ void operator()(f32x4 (&acc)[2][2][4][2], int pm, int pn, int wr_, int wc_, int fr_, int fq_, bf16_t* shm, int tid) const {
;     ...
;             s1[ai * 4 + m] += (xv[0] + xv[1]) + (xv[2] + xv[3]);
;             s2[ai * 4 + m] += (xv[0] * xv[0] + xv[1] * xv[1]) + (xv[2] * xv[2] + xv[3] * xv[3]);
;           }
;       }
; #pragma unroll
;     for (int i = 0; i < 8; ++i) {
;       s1[i] += __shfl_xor(s1[i], 16); s1[i] += __shfl_xor(s1[i], 32);
;       s2[i] += __shfl_xor(s2[i], 16); s2[i] += __shfl_xor(s2[i], 32);
;       if (fq == 0) red[((i >> 2) * 128 + wr * 64 + (i & 3) * 16 + fr) * 4 + wc] = (f2_t){s1[i], s2[i]};
.LBB0_547:
	v_mov_b32_e32 v134, v128
	v_mov_b32_e32 v135, v126
	v_mov_b32_e32 v136, v129
	v_mov_b32_e32 v137, v126
	v_pk_add_f32 v[138:139], v[134:135], v[136:137]
	v_pk_mul_f32 v[134:135], v[134:135], v[136:137]
	v_pk_mul_f32 v[136:137], v[126:127], v[126:127]
	v_mov_b32_e32 v139, v135
	v_pk_add_f32 v[134:135], v[126:127], v[126:127] op_sel:[1,0]
	v_mul_f32_e32 v136, v128, v128
	v_mov_b32_e32 v135, v137
	v_pk_fma_f32 v[136:137], v[128:129], v[128:129], v[136:137] op_sel_hi:[1,1,0]
	v_pk_add_f32 v[134:135], v[134:135], v[138:139]
	v_mov_b32_e32 v136, v1
	v_pk_add_f32 v[134:135], v[134:135], v[136:137]
	v_mul_f32_e32 v137, v82, v82
	v_mul_f32_e32 v139, v83, v83
	v_mul_f32_e32 v141, v84, v84
	v_mul_f32_e32 v151, v85, v85
	v_mov_b32_e32 v136, v82
	v_mov_b32_e32 v138, v83
	v_mov_b32_e32 v140, v84
	v_mov_b32_e32 v150, v85
	v_pk_add_f32 v[136:137], v[136:137], v[138:139]
	v_pk_add_f32 v[138:139], v[140:141], v[150:151]
	v_mul_f32_e32 v141, v100, v100
	v_pk_add_f32 v[136:137], v[136:137], v[138:139]
	v_mul_f32_e32 v139, v99, v99
	v_pk_add_f32 v[134:135], v[134:135], v[136:137]
	v_mul_f32_e32 v137, v98, v98
	v_mul_f32_e32 v151, v101, v101
	v_mov_b32_e32 v136, v98
	v_mov_b32_e32 v138, v99
	v_mov_b32_e32 v140, v100
	v_mov_b32_e32 v150, v101
	v_pk_add_f32 v[136:137], v[136:137], v[138:139]
	v_pk_add_f32 v[138:139], v[140:141], v[150:151]
	v_mul_f32_e32 v141, v116, v116
	v_pk_add_f32 v[136:137], v[136:137], v[138:139]
	v_mul_f32_e32 v139, v115, v115
	v_pk_add_f32 v[134:135], v[134:135], v[136:137]
	v_mul_f32_e32 v137, v114, v114
	v_mul_f32_e32 v151, v117, v117
	v_mov_b32_e32 v136, v114
	v_mov_b32_e32 v138, v115
	v_mov_b32_e32 v140, v116
	v_mov_b32_e32 v150, v117
	v_pk_add_f32 v[136:137], v[136:137], v[138:139]
	v_pk_add_f32 v[138:139], v[140:141], v[150:151]
	v_readlane_b32 s0, v253, 26
	v_pk_add_f32 v[136:137], v[136:137], v[138:139]
	v_pk_add_f32 v[136:137], v[134:135], v[136:137]
	v_and_b32_e32 v131, 64, v226
	v_xor_b32_e32 v130, 16, v226
	v_add_u32_e32 v132, 64, v131
	v_cmp_lt_i32_e32 vcc, v130, v132
	v_xor_b32_e32 v133, 32, v226
	v_cndmask_b32_e32 v130, v226, v130, vcc
	v_lshlrev_b32_e32 v134, 2, v130
	v_mov_b32_e32 v130, v136
	v_mov_b32_e32 v131, v137
	s_nop 1
	v_permlane16_swap_b32_e32 v130, v136
	v_permlane16_swap_b32_e32 v131, v137
	v_cmp_lt_i32_e32 vcc, v133, v132
	v_or_b32_e32 v160, v242, v149
	s_waitcnt lgkmcnt(0)
	v_pk_add_f32 v[130:131], v[136:137], v[130:131]
	v_cndmask_b32_e32 v132, v226, v133, vcc
	v_lshlrev_b32_e32 v135, 2, v132
	v_mov_b32_e32 v132, v130
	v_mov_b32_e32 v133, v131
	s_nop 1
	v_permlane32_swap_b32_e32 v132, v130
	v_permlane32_swap_b32_e32 v133, v131
	v_lshl_add_u32 v136, v243, 3, s0
	v_cmp_eq_u32_e32 vcc, 0, v244
	v_lshl_add_u32 v137, v160, 5, v136
	s_and_saveexec_b64 s[0:1], vcc
	s_cbranch_execz .LBB0_549
	s_waitcnt lgkmcnt(0)
	v_pk_add_f32 v[130:131], v[130:131], v[132:133]
	ds_write_b64 v137, v[130:131]
.LBB0_549:
	s_or_b64 exec, exec, s[0:1]
	v_mov_b32_e32 v130, v112
	v_mov_b32_e32 v131, v110
	s_waitcnt lgkmcnt(1)
	v_mov_b32_e32 v132, v113
	s_waitcnt lgkmcnt(0)
	v_mov_b32_e32 v133, v110
	v_pk_add_f32 v[138:139], v[130:131], v[132:133]
	v_pk_mul_f32 v[130:131], v[130:131], v[132:133]
	v_pk_mul_f32 v[132:133], v[110:111], v[110:111]
	v_mov_b32_e32 v139, v131
	v_pk_add_f32 v[130:131], v[110:111], v[110:111] op_sel:[1,0]
	v_mul_f32_e32 v132, v112, v112
	v_mov_b32_e32 v131, v133
	v_pk_fma_f32 v[132:133], v[112:113], v[112:113], v[132:133] op_sel_hi:[1,1,0]
	v_pk_add_f32 v[130:131], v[130:131], v[138:139]
	v_mov_b32_e32 v132, v1
	v_pk_add_f32 v[130:131], v[130:131], v[132:133]
	v_mul_f32_e32 v133, v86, v86
	v_mul_f32_e32 v139, v87, v87
	v_mul_f32_e32 v141, v88, v88
	v_mul_f32_e32 v143, v89, v89
	v_mov_b32_e32 v132, v86
	v_mov_b32_e32 v138, v87
	v_mov_b32_e32 v140, v88
	v_mov_b32_e32 v142, v89
	v_pk_add_f32 v[132:133], v[132:133], v[138:139]
	v_pk_add_f32 v[138:139], v[140:141], v[142:143]
	v_mul_f32_e32 v141, v104, v104
	v_pk_add_f32 v[132:133], v[132:133], v[138:139]
	v_mul_f32_e32 v139, v103, v103
	v_pk_add_f32 v[130:131], v[130:131], v[132:133]
	v_mul_f32_e32 v133, v102, v102
	v_mul_f32_e32 v143, v105, v105
	v_mov_b32_e32 v132, v102
	v_mov_b32_e32 v138, v103
	v_mov_b32_e32 v140, v104
	v_mov_b32_e32 v142, v105
	v_pk_add_f32 v[132:133], v[132:133], v[138:139]
	v_pk_add_f32 v[138:139], v[140:141], v[142:143]
	v_mul_f32_e32 v141, v120, v120
	v_pk_add_f32 v[132:133], v[132:133], v[138:139]
	v_mul_f32_e32 v139, v119, v119
	v_pk_add_f32 v[130:131], v[130:131], v[132:133]
	v_mul_f32_e32 v133, v118, v118
	v_mul_f32_e32 v143, v121, v121
	v_mov_b32_e32 v132, v118
	v_mov_b32_e32 v138, v119
	v_mov_b32_e32 v140, v120
	v_mov_b32_e32 v142, v121
	v_pk_add_f32 v[132:133], v[132:133], v[138:139]
	v_pk_add_f32 v[138:139], v[140:141], v[142:143]
	s_nop 0
	v_pk_add_f32 v[132:133], v[132:133], v[138:139]
	s_nop 0
	v_pk_add_f32 v[130:131], v[130:131], v[132:133]
	v_mov_b32_e32 v132, v130
	v_mov_b32_e32 v133, v131
	s_nop 1
	v_permlane16_swap_b32_e32 v132, v130
	v_permlane16_swap_b32_e32 v133, v131
	s_waitcnt lgkmcnt(0)
	v_pk_add_f32 v[130:131], v[130:131], v[132:133]
	v_mov_b32_e32 v132, v130
	v_mov_b32_e32 v133, v131
	s_nop 1
	v_permlane32_swap_b32_e32 v132, v130
	v_permlane32_swap_b32_e32 v133, v131
	s_and_saveexec_b64 s[0:1], vcc
	s_cbranch_execz .LBB0_551
	s_waitcnt lgkmcnt(0)
	v_pk_add_f32 v[130:131], v[130:131], v[132:133]
	ds_write_b64 v137, v[130:131] offset:512
;   __device__ __forceinline__ void operator()(f32x4 (&acc)[2][2][4][2], int pm, int pn, int wr_, int wc_, int fr_, int fq_, bf16_t* shm, int tid) const {
;     ...
;             s1[ai * 4 + m] += (xv[0] + xv[1]) + (xv[2] + xv[3]);
;             s2[ai * 4 + m] += (xv[0] * xv[0] + xv[1] * xv[1]) + (xv[2] * xv[2] + xv[3] * xv[3]);
;           }
;       }
; #pragma unroll
;     for (int i = 0; i < 8; ++i) {
;       s1[i] += __shfl_xor(s1[i], 16); s1[i] += __shfl_xor(s1[i], 32);
;       s2[i] += __shfl_xor(s2[i], 16); s2[i] += __shfl_xor(s2[i], 32);
;       if (fq == 0) red[((i >> 2) * 128 + wr * 64 + (i & 3) * 16 + fr) * 4 + wc] = (f2_t){s1[i], s2[i]};
.LBB0_551:
	s_or_b64 exec, exec, s[0:1]
	v_mov_b32_e32 v130, v96
	v_mov_b32_e32 v131, v94
	s_waitcnt lgkmcnt(1)
	v_mov_b32_e32 v132, v97
	s_waitcnt lgkmcnt(0)
	v_mov_b32_e32 v133, v94
	v_pk_add_f32 v[138:139], v[130:131], v[132:133]
	v_pk_mul_f32 v[130:131], v[130:131], v[132:133]
	v_pk_mul_f32 v[132:133], v[94:95], v[94:95]
	v_mov_b32_e32 v139, v131
	v_pk_add_f32 v[130:131], v[94:95], v[94:95] op_sel:[1,0]
	v_mul_f32_e32 v132, v96, v96
	v_mov_b32_e32 v131, v133
	v_pk_fma_f32 v[132:133], v[96:97], v[96:97], v[132:133] op_sel_hi:[1,1,0]
	v_pk_add_f32 v[130:131], v[130:131], v[138:139]
	v_mov_b32_e32 v132, v1
	v_pk_add_f32 v[130:131], v[130:131], v[132:133]
	v_mul_f32_e32 v133, v78, v78
	v_mul_f32_e32 v139, v79, v79
	v_mul_f32_e32 v141, v80, v80
	v_mul_f32_e32 v143, v81, v81
	v_mov_b32_e32 v132, v78
	v_mov_b32_e32 v138, v79
	v_mov_b32_e32 v140, v80
	v_mov_b32_e32 v142, v81
	v_pk_add_f32 v[132:133], v[132:133], v[138:139]
	v_pk_add_f32 v[138:139], v[140:141], v[142:143]
	v_mul_f32_e32 v141, v92, v92
	v_pk_add_f32 v[132:133], v[132:133], v[138:139]
	v_mul_f32_e32 v139, v91, v91
	v_pk_add_f32 v[130:131], v[130:131], v[132:133]
	v_mul_f32_e32 v133, v90, v90
	v_mul_f32_e32 v143, v93, v93
	v_mov_b32_e32 v132, v90
	v_mov_b32_e32 v138, v91
	v_mov_b32_e32 v140, v92
	v_mov_b32_e32 v142, v93
	v_pk_add_f32 v[132:133], v[132:133], v[138:139]
	v_pk_add_f32 v[138:139], v[140:141], v[142:143]
	v_mul_f32_e32 v141, v108, v108
	v_pk_add_f32 v[132:133], v[132:133], v[138:139]
	v_mul_f32_e32 v139, v107, v107
	v_pk_add_f32 v[130:131], v[130:131], v[132:133]
	v_mul_f32_e32 v133, v106, v106
	v_mul_f32_e32 v143, v109, v109
	v_mov_b32_e32 v132, v106
	v_mov_b32_e32 v138, v107
	v_mov_b32_e32 v140, v108
	v_mov_b32_e32 v142, v109
	v_pk_add_f32 v[132:133], v[132:133], v[138:139]
	v_pk_add_f32 v[138:139], v[140:141], v[142:143]
	s_nop 0
	v_pk_add_f32 v[132:133], v[132:133], v[138:139]
	s_nop 0
	v_pk_add_f32 v[130:131], v[130:131], v[132:133]
	v_mov_b32_e32 v132, v130
	v_mov_b32_e32 v133, v131
	s_nop 1
	v_permlane16_swap_b32_e32 v132, v130
	v_permlane16_swap_b32_e32 v133, v131
	s_waitcnt lgkmcnt(0)
	v_pk_add_f32 v[130:131], v[130:131], v[132:133]
	v_mov_b32_e32 v132, v130
	v_mov_b32_e32 v133, v131
	s_nop 1
	v_permlane32_swap_b32_e32 v132, v130
	v_permlane32_swap_b32_e32 v133, v131
	s_and_saveexec_b64 s[0:1], vcc
	s_cbranch_execz .LBB0_553
	s_waitcnt lgkmcnt(0)
	v_pk_add_f32 v[130:131], v[130:131], v[132:133]
	ds_write_b64 v137, v[130:131] offset:1024
.LBB0_553:
	s_or_b64 exec, exec, s[0:1]
	v_mov_b32_e32 v130, v4
	v_mov_b32_e32 v131, v2
	s_waitcnt lgkmcnt(1)
	v_mov_b32_e32 v132, v5
	s_waitcnt lgkmcnt(0)
	v_mov_b32_e32 v133, v2
	v_pk_add_f32 v[138:139], v[130:131], v[132:133]
	v_pk_mul_f32 v[130:131], v[130:131], v[132:133]
	v_pk_mul_f32 v[132:133], v[2:3], v[2:3]
	v_mov_b32_e32 v139, v131
	v_pk_add_f32 v[130:131], v[2:3], v[2:3] op_sel:[1,0]
	v_mul_f32_e32 v132, v4, v4
	v_mov_b32_e32 v131, v133
	v_pk_fma_f32 v[132:133], v[4:5], v[4:5], v[132:133] op_sel_hi:[1,1,0]
	v_pk_add_f32 v[130:131], v[130:131], v[138:139]
	v_mov_b32_e32 v132, v1
	v_pk_add_f32 v[130:131], v[130:131], v[132:133]
	v_mul_f32_e32 v133, v10, v10
	v_mul_f32_e32 v139, v11, v11
	v_mul_f32_e32 v141, v12, v12
	v_mul_f32_e32 v143, v13, v13
	v_mov_b32_e32 v132, v10
	v_mov_b32_e32 v138, v11
	v_mov_b32_e32 v140, v12
	v_mov_b32_e32 v142, v13
	v_pk_add_f32 v[132:133], v[132:133], v[138:139]
	v_pk_add_f32 v[138:139], v[140:141], v[142:143]
	v_mul_f32_e32 v141, v24, v24
	v_pk_add_f32 v[132:133], v[132:133], v[138:139]
	v_mul_f32_e32 v139, v23, v23
	v_pk_add_f32 v[130:131], v[130:131], v[132:133]
	v_mul_f32_e32 v133, v22, v22
	v_mul_f32_e32 v143, v25, v25
	v_mov_b32_e32 v132, v22
	v_mov_b32_e32 v138, v23
	v_mov_b32_e32 v140, v24
	v_mov_b32_e32 v142, v25
	v_pk_add_f32 v[132:133], v[132:133], v[138:139]
	v_pk_add_f32 v[138:139], v[140:141], v[142:143]
	v_mul_f32_e32 v141, v40, v40
	v_pk_add_f32 v[132:133], v[132:133], v[138:139]
	v_mul_f32_e32 v139, v39, v39
	v_pk_add_f32 v[130:131], v[130:131], v[132:133]
	v_mul_f32_e32 v133, v38, v38
	v_mul_f32_e32 v143, v41, v41
	v_mov_b32_e32 v132, v38
	v_mov_b32_e32 v138, v39
	v_mov_b32_e32 v140, v40
	v_mov_b32_e32 v142, v41
	v_pk_add_f32 v[132:133], v[132:133], v[138:139]
	v_pk_add_f32 v[138:139], v[140:141], v[142:143]
	s_nop 0
	v_pk_add_f32 v[132:133], v[132:133], v[138:139]
	s_nop 0
	v_pk_add_f32 v[130:131], v[130:131], v[132:133]
	v_mov_b32_e32 v132, v130
	v_mov_b32_e32 v133, v131
	s_nop 1
	v_permlane16_swap_b32_e32 v132, v130
	v_permlane16_swap_b32_e32 v133, v131
	s_waitcnt lgkmcnt(0)
	v_pk_add_f32 v[130:131], v[130:131], v[132:133]
	v_mov_b32_e32 v132, v130
	v_mov_b32_e32 v133, v131
	s_nop 1
	v_permlane32_swap_b32_e32 v132, v130
	v_permlane32_swap_b32_e32 v133, v131
	s_and_saveexec_b64 s[0:1], vcc
	s_cbranch_execz .LBB0_555
	s_waitcnt lgkmcnt(0)
	v_pk_add_f32 v[130:131], v[130:131], v[132:133]
	ds_write_b64 v137, v[130:131] offset:1536
;   __device__ __forceinline__ void operator()(f32x4 (&acc)[2][2][4][2], int pm, int pn, int wr_, int wc_, int fr_, int fq_, bf16_t* shm, int tid) const {
;     ...
;             s1[ai * 4 + m] += (xv[0] + xv[1]) + (xv[2] + xv[3]);
;             s2[ai * 4 + m] += (xv[0] * xv[0] + xv[1] * xv[1]) + (xv[2] * xv[2] + xv[3] * xv[3]);
;           }
;       }
; #pragma unroll
;     for (int i = 0; i < 8; ++i) {
;       s1[i] += __shfl_xor(s1[i], 16); s1[i] += __shfl_xor(s1[i], 32);
;       s2[i] += __shfl_xor(s2[i], 16); s2[i] += __shfl_xor(s2[i], 32);
;       if (fq == 0) red[((i >> 2) * 128 + wr * 64 + (i & 3) * 16 + fr) * 4 + wc] = (f2_t){s1[i], s2[i]};
.LBB0_555:
	s_or_b64 exec, exec, s[0:1]
	v_mov_b32_e32 v130, v8
	v_mov_b32_e32 v131, v6
	s_waitcnt lgkmcnt(1)
	v_mov_b32_e32 v132, v9
	s_waitcnt lgkmcnt(0)
	v_mov_b32_e32 v133, v6
	v_pk_add_f32 v[138:139], v[130:131], v[132:133]
	v_pk_mul_f32 v[130:131], v[130:131], v[132:133]
	v_pk_mul_f32 v[132:133], v[6:7], v[6:7]
	v_mov_b32_e32 v139, v131
	v_pk_add_f32 v[130:131], v[6:7], v[6:7] op_sel:[1,0]
	v_mul_f32_e32 v132, v8, v8
	v_mov_b32_e32 v131, v133
	v_pk_fma_f32 v[132:133], v[8:9], v[8:9], v[132:133] op_sel_hi:[1,1,0]
	v_pk_add_f32 v[130:131], v[130:131], v[138:139]
	v_mov_b32_e32 v132, v1
	v_pk_add_f32 v[130:131], v[130:131], v[132:133]
	v_mul_f32_e32 v133, v18, v18
	v_mul_f32_e32 v139, v19, v19
	v_mul_f32_e32 v141, v20, v20
	v_mul_f32_e32 v143, v21, v21
	v_mov_b32_e32 v132, v18
	v_mov_b32_e32 v138, v19
	v_mov_b32_e32 v140, v20
	v_mov_b32_e32 v142, v21
	v_pk_add_f32 v[132:133], v[132:133], v[138:139]
	v_pk_add_f32 v[138:139], v[140:141], v[142:143]
	v_mul_f32_e32 v141, v36, v36
	v_pk_add_f32 v[132:133], v[132:133], v[138:139]
	v_mul_f32_e32 v139, v35, v35
	v_pk_add_f32 v[130:131], v[130:131], v[132:133]
	v_mul_f32_e32 v133, v34, v34
	v_mul_f32_e32 v143, v37, v37
	v_mov_b32_e32 v132, v34
	v_mov_b32_e32 v138, v35
	v_mov_b32_e32 v140, v36
	v_mov_b32_e32 v142, v37
	v_pk_add_f32 v[132:133], v[132:133], v[138:139]
	v_pk_add_f32 v[138:139], v[140:141], v[142:143]
	v_mul_f32_e32 v141, v52, v52
	v_pk_add_f32 v[132:133], v[132:133], v[138:139]
	v_mul_f32_e32 v139, v51, v51
	v_pk_add_f32 v[130:131], v[130:131], v[132:133]
	v_mul_f32_e32 v133, v50, v50
	v_mul_f32_e32 v143, v53, v53
	v_mov_b32_e32 v132, v50
	v_mov_b32_e32 v138, v51
	v_mov_b32_e32 v140, v52
	v_mov_b32_e32 v142, v53
	v_pk_add_f32 v[132:133], v[132:133], v[138:139]
	v_pk_add_f32 v[138:139], v[140:141], v[142:143]
	v_add_u32_e32 v137, v242, v149
	v_pk_add_f32 v[132:133], v[132:133], v[138:139]
	v_lshl_add_u32 v136, v137, 5, v136
	v_pk_add_f32 v[130:131], v[130:131], v[132:133]
	v_mov_b32_e32 v132, v130
	v_mov_b32_e32 v133, v131
	s_nop 1
	v_permlane16_swap_b32_e32 v132, v130
	v_permlane16_swap_b32_e32 v133, v131
	s_waitcnt lgkmcnt(0)
	v_pk_add_f32 v[130:131], v[130:131], v[132:133]
	v_mov_b32_e32 v132, v130
	v_mov_b32_e32 v133, v131
	s_nop 1
	v_permlane32_swap_b32_e32 v132, v130
	v_permlane32_swap_b32_e32 v133, v131
	s_and_saveexec_b64 s[0:1], vcc
	s_cbranch_execz .LBB0_557
	s_waitcnt lgkmcnt(0)
	v_pk_add_f32 v[130:131], v[130:131], v[132:133]
	ds_write_b64 v136, v[130:131] offset:4096
.LBB0_557:
	s_or_b64 exec, exec, s[0:1]
	v_mov_b32_e32 v130, v16
	v_mov_b32_e32 v131, v14
	s_waitcnt lgkmcnt(1)
	v_mov_b32_e32 v132, v17
	s_waitcnt lgkmcnt(0)
	v_mov_b32_e32 v133, v14
	v_pk_add_f32 v[138:139], v[130:131], v[132:133]
	v_pk_mul_f32 v[130:131], v[130:131], v[132:133]
	v_pk_mul_f32 v[132:133], v[14:15], v[14:15]
	v_mov_b32_e32 v139, v131
	v_pk_add_f32 v[130:131], v[14:15], v[14:15] op_sel:[1,0]
	v_mul_f32_e32 v132, v16, v16
	v_mov_b32_e32 v131, v133
	v_pk_fma_f32 v[132:133], v[16:17], v[16:17], v[132:133] op_sel_hi:[1,1,0]
	v_pk_add_f32 v[130:131], v[130:131], v[138:139]
	v_mov_b32_e32 v132, v1
	v_pk_add_f32 v[130:131], v[130:131], v[132:133]
	v_mul_f32_e32 v133, v26, v26
	v_mul_f32_e32 v139, v27, v27
	v_mul_f32_e32 v141, v28, v28
	v_mul_f32_e32 v143, v29, v29
	v_mov_b32_e32 v132, v26
	v_mov_b32_e32 v138, v27
	v_mov_b32_e32 v140, v28
	v_mov_b32_e32 v142, v29
	v_pk_add_f32 v[132:133], v[132:133], v[138:139]
	v_pk_add_f32 v[138:139], v[140:141], v[142:143]
	v_mul_f32_e32 v141, v44, v44
	v_pk_add_f32 v[132:133], v[132:133], v[138:139]
	v_mul_f32_e32 v139, v43, v43
	v_pk_add_f32 v[130:131], v[130:131], v[132:133]
	v_mul_f32_e32 v133, v42, v42
	v_mul_f32_e32 v143, v45, v45
	v_mov_b32_e32 v132, v42
	v_mov_b32_e32 v138, v43
	v_mov_b32_e32 v140, v44
	v_mov_b32_e32 v142, v45
	v_pk_add_f32 v[132:133], v[132:133], v[138:139]
	v_pk_add_f32 v[138:139], v[140:141], v[142:143]
	v_mul_f32_e32 v141, v60, v60
	v_pk_add_f32 v[132:133], v[132:133], v[138:139]
	v_mul_f32_e32 v139, v59, v59
	v_pk_add_f32 v[130:131], v[130:131], v[132:133]
	v_mul_f32_e32 v133, v58, v58
	v_mul_f32_e32 v143, v61, v61
	v_mov_b32_e32 v132, v58
	v_mov_b32_e32 v138, v59
	v_mov_b32_e32 v140, v60
	v_mov_b32_e32 v142, v61
	v_pk_add_f32 v[132:133], v[132:133], v[138:139]
	v_pk_add_f32 v[138:139], v[140:141], v[142:143]
	s_nop 0
	v_pk_add_f32 v[132:133], v[132:133], v[138:139]
	s_nop 0
	v_pk_add_f32 v[130:131], v[130:131], v[132:133]
	v_mov_b32_e32 v132, v130
	v_mov_b32_e32 v133, v131
	s_nop 1
	v_permlane16_swap_b32_e32 v132, v130
	v_permlane16_swap_b32_e32 v133, v131
	s_waitcnt lgkmcnt(0)
	v_pk_add_f32 v[130:131], v[130:131], v[132:133]
	v_mov_b32_e32 v132, v130
	v_mov_b32_e32 v133, v131
	s_nop 1
	v_permlane32_swap_b32_e32 v132, v130
	v_permlane32_swap_b32_e32 v133, v131
	s_and_saveexec_b64 s[0:1], vcc
	s_cbranch_execz .LBB0_559
	s_waitcnt lgkmcnt(0)
	v_pk_add_f32 v[130:131], v[130:131], v[132:133]
	ds_write_b64 v136, v[130:131] offset:4608
;   __device__ __forceinline__ void operator()(f32x4 (&acc)[2][2][4][2], int pm, int pn, int wr_, int wc_, int fr_, int fq_, bf16_t* shm, int tid) const {
;     ...
;             s1[ai * 4 + m] += (xv[0] + xv[1]) + (xv[2] + xv[3]);
;             s2[ai * 4 + m] += (xv[0] * xv[0] + xv[1] * xv[1]) + (xv[2] * xv[2] + xv[3] * xv[3]);
;           }
;       }
; #pragma unroll
;     for (int i = 0; i < 8; ++i) {
;       s1[i] += __shfl_xor(s1[i], 16); s1[i] += __shfl_xor(s1[i], 32);
;       s2[i] += __shfl_xor(s2[i], 16); s2[i] += __shfl_xor(s2[i], 32);
;       if (fq == 0) red[((i >> 2) * 128 + wr * 64 + (i & 3) * 16 + fr) * 4 + wc] = (f2_t){s1[i], s2[i]};
.LBB0_559:
	s_or_b64 exec, exec, s[0:1]
	v_mov_b32_e32 v130, v32
	v_mov_b32_e32 v131, v30
	s_waitcnt lgkmcnt(1)
	v_mov_b32_e32 v132, v33
	s_waitcnt lgkmcnt(0)
	v_mov_b32_e32 v133, v30
	v_pk_add_f32 v[138:139], v[130:131], v[132:133]
	v_pk_mul_f32 v[130:131], v[130:131], v[132:133]
	v_pk_mul_f32 v[132:133], v[30:31], v[30:31]
	v_mov_b32_e32 v139, v131
	v_pk_add_f32 v[130:131], v[30:31], v[30:31] op_sel:[1,0]
	v_mul_f32_e32 v132, v32, v32
	v_mov_b32_e32 v131, v133
	v_pk_fma_f32 v[132:133], v[32:33], v[32:33], v[132:133] op_sel_hi:[1,1,0]
	v_pk_add_f32 v[130:131], v[130:131], v[138:139]
	v_mov_b32_e32 v132, v1
	v_pk_add_f32 v[130:131], v[130:131], v[132:133]
	v_mul_f32_e32 v133, v46, v46
	v_mul_f32_e32 v139, v47, v47
	v_mul_f32_e32 v141, v48, v48
	v_mul_f32_e32 v143, v49, v49
	v_mov_b32_e32 v132, v46
	v_mov_b32_e32 v138, v47
	v_mov_b32_e32 v140, v48
	v_mov_b32_e32 v142, v49
	v_pk_add_f32 v[132:133], v[132:133], v[138:139]
	v_pk_add_f32 v[138:139], v[140:141], v[142:143]
	v_mul_f32_e32 v141, v64, v64
	v_pk_add_f32 v[132:133], v[132:133], v[138:139]
	v_mul_f32_e32 v139, v63, v63
	v_pk_add_f32 v[130:131], v[130:131], v[132:133]
	v_mul_f32_e32 v133, v62, v62
	v_mul_f32_e32 v143, v65, v65
	v_mov_b32_e32 v132, v62
	v_mov_b32_e32 v138, v63
	v_mov_b32_e32 v140, v64
	v_mov_b32_e32 v142, v65
	v_pk_add_f32 v[132:133], v[132:133], v[138:139]
	v_pk_add_f32 v[138:139], v[140:141], v[142:143]
	v_mul_f32_e32 v141, v72, v72
	v_pk_add_f32 v[132:133], v[132:133], v[138:139]
	v_mul_f32_e32 v139, v71, v71
	v_pk_add_f32 v[130:131], v[130:131], v[132:133]
	v_mul_f32_e32 v133, v70, v70
	v_mul_f32_e32 v143, v73, v73
	v_mov_b32_e32 v132, v70
	v_mov_b32_e32 v138, v71
	v_mov_b32_e32 v140, v72
	v_mov_b32_e32 v142, v73
	v_pk_add_f32 v[132:133], v[132:133], v[138:139]
	v_pk_add_f32 v[138:139], v[140:141], v[142:143]
	s_nop 0
	v_pk_add_f32 v[132:133], v[132:133], v[138:139]
	s_nop 0
	v_pk_add_f32 v[130:131], v[130:131], v[132:133]
	v_mov_b32_e32 v132, v130
	v_mov_b32_e32 v133, v131
	s_nop 1
	v_permlane16_swap_b32_e32 v132, v130
	v_permlane16_swap_b32_e32 v133, v131
	s_waitcnt lgkmcnt(0)
	v_pk_add_f32 v[130:131], v[130:131], v[132:133]
	v_mov_b32_e32 v132, v130
	v_mov_b32_e32 v133, v131
	s_nop 1
	v_permlane32_swap_b32_e32 v132, v130
	v_permlane32_swap_b32_e32 v133, v131
	s_and_saveexec_b64 s[0:1], vcc
	s_cbranch_execz .LBB0_561
	s_waitcnt lgkmcnt(0)
	v_pk_add_f32 v[130:131], v[130:131], v[132:133]
	ds_write_b64 v136, v[130:131] offset:5120
.LBB0_561:
	s_or_b64 exec, exec, s[0:1]
	v_mov_b32_e32 v130, v56
	v_mov_b32_e32 v131, v54
	s_waitcnt lgkmcnt(1)
	v_mov_b32_e32 v132, v57
	s_waitcnt lgkmcnt(0)
	v_mov_b32_e32 v133, v54
	v_pk_add_f32 v[138:139], v[130:131], v[132:133]
	v_pk_mul_f32 v[130:131], v[130:131], v[132:133]
	v_pk_mul_f32 v[132:133], v[54:55], v[54:55]
	v_mov_b32_e32 v139, v131
	v_pk_add_f32 v[130:131], v[54:55], v[54:55] op_sel:[1,0]
	v_mul_f32_e32 v132, v56, v56
	v_mov_b32_e32 v131, v133
	v_pk_fma_f32 v[132:133], v[56:57], v[56:57], v[132:133] op_sel_hi:[1,1,0]
	v_pk_add_f32 v[130:131], v[130:131], v[138:139]
	v_mov_b32_e32 v132, v1
	v_pk_add_f32 v[130:131], v[130:131], v[132:133]
	v_mul_f32_e32 v133, v66, v66
	v_mul_f32_e32 v139, v67, v67
	v_mul_f32_e32 v141, v68, v68
	v_mul_f32_e32 v143, v69, v69
	v_mov_b32_e32 v132, v66
	v_mov_b32_e32 v138, v67
	v_mov_b32_e32 v140, v68
	v_mov_b32_e32 v142, v69
	v_pk_add_f32 v[132:133], v[132:133], v[138:139]
	v_pk_add_f32 v[138:139], v[140:141], v[142:143]
	v_mul_f32_e32 v141, v76, v76
	v_pk_add_f32 v[132:133], v[132:133], v[138:139]
	v_mul_f32_e32 v139, v75, v75
	v_pk_add_f32 v[130:131], v[130:131], v[132:133]
	v_mul_f32_e32 v133, v74, v74
	v_mul_f32_e32 v143, v77, v77
	v_mov_b32_e32 v132, v74
	v_mov_b32_e32 v138, v75
	v_mov_b32_e32 v140, v76
	v_mov_b32_e32 v142, v77
	v_pk_add_f32 v[132:133], v[132:133], v[138:139]
	v_pk_add_f32 v[138:139], v[140:141], v[142:143]
	v_mul_f32_e32 v141, v124, v124
	v_pk_add_f32 v[132:133], v[132:133], v[138:139]
	v_mul_f32_e32 v139, v123, v123
	v_pk_add_f32 v[130:131], v[130:131], v[132:133]
	v_mul_f32_e32 v133, v122, v122
	v_mul_f32_e32 v143, v125, v125
	v_mov_b32_e32 v132, v122
	v_mov_b32_e32 v138, v123
	v_mov_b32_e32 v140, v124
	v_mov_b32_e32 v142, v125
	v_pk_add_f32 v[132:133], v[132:133], v[138:139]
	v_pk_add_f32 v[138:139], v[140:141], v[142:143]
	s_nop 0
	v_pk_add_f32 v[132:133], v[132:133], v[138:139]
	s_nop 0
	v_pk_add_f32 v[130:131], v[130:131], v[132:133]
	v_mov_b32_e32 v132, v130
	v_mov_b32_e32 v133, v131
	s_nop 1
	v_permlane16_swap_b32_e32 v132, v130
	v_permlane16_swap_b32_e32 v133, v131
	s_waitcnt lgkmcnt(0)
	v_pk_add_f32 v[130:131], v[130:131], v[132:133]
	v_mov_b32_e32 v132, v130
	v_mov_b32_e32 v133, v131
	s_nop 1
	v_permlane32_swap_b32_e32 v132, v130
	v_permlane32_swap_b32_e32 v133, v131
	s_and_saveexec_b64 s[0:1], vcc
	s_cbranch_execz .LBB0_563
	s_waitcnt lgkmcnt(0)
	v_pk_add_f32 v[130:131], v[130:131], v[132:133]
	ds_write_b64 v136, v[130:131] offset:5632
